# R1S / R2 units placed on the XCD half that wrote their q,k,v heads (with the interleaved input-projection tiles)
# speedup vs baseline: 1.0024x; 1.0024x over previous
; __device__ __forceinline__ void r2_phase(KP p, LAS unsigned char* lds, int G, int bid, int wv) {
;     int tid_ = wv * 64 + (int)__builtin_amdgcn_mbcnt_hi(~0u, __builtin_amdgcn_mbcnt_lo(~0u, 0u)); asm volatile("" : "+v"(tid_));
;     const int tid = tid_, wid = tid >> 6, lane = tid & 63, fr = lane & 15, fq = lane >> 4;
;     unsigned char* ws = p->ws;
;     const bf16_t* qn = (const bf16_t*)(ws + WS_Q); const bf16_t* kn = (const bf16_t*)(ws + WS_K); const bf16_t* vT = (const bf16_t*)(ws + WS_VT);
;     const bf16_t* ST = (const bf16_t*)(ws + WS_ST); const bf16_t* pr = (const bf16_t*)(ws + WS_PR); bf16_t* Y = (bf16_t*)(ws + WS_Y);
;     LAS unsigned char* Ks = lds; LAS unsigned char* Vs = lds + 34816; LAS unsigned char* Pw = lds + 69632 + wid * 4352;
;     for (int u = bid; u < 512; u += G) {
;         const int bh = u >> 4, n = u & 15, b = bh >> 3, h = bh & 7;
;         const size_t row0 = (size_t)b * SEQ + n * 128;
;         float lf = log2_gamma(p->in[18][h]), lb = log2_gamma(p->in[19][h]);
;         asm volatile("" : "+v"(lf), "+v"(lb));
;         {
;             u32x4 kq[4], vq[4];
; #pragma unroll
;             for (int q = 0; q < 4; ++q) { const int c = tid + 512 * q, r = c >> 4, c16 = c & 15;
;                 kq[q] = *(const u32x4*)(kn + (row0 + r) * 1024 + h * 128 + c16 * 8);
;                 vq[q] = *(const u32x4*)(vT + ((size_t)(bh * 18 + 2 + n) * 128 + r) * 128 + c16 * 8); }
; #pragma unroll
;             for (int q = 0; q < 4; ++q) { const int c = tid + 512 * q, r = c >> 4, c16 = c & 15;
;                 *(LAS u32x4*)(Ks + r * 272 + c16 * 16) = kq[q]; *(LAS u32x4*)(Vs + r * 272 + c16 * 16) = vq[q]; }
;         }
;         bf16x8 qf[4];
; #pragma unroll
;         for (int ks = 0; ks < 4; ++ks) qf[ks] = *(const bf16x8*)(qn + (row0 + 16 * wid + fr) * 1024 + h * 128 + 32 * ks + 8 * fq);
;         __syncthreads();
;         f32x4 sc[8];
; #pragma unroll
;         for (int i = 0; i < 8; ++i) sc[i] = (f32x4){0.f, 0.f, 0.f, 0.f};
; #pragma unroll
;         for (int ks = 0; ks < 4; ++ks)
; #pragma unroll
;             for (int i = 0; i < 8; ++i) {
;                 const bf16x8 kf = *(const LAS bf16x8*)(Ks + (16 * i + fr) * 272 + (32 * ks + 8 * fq) * 2);
;                 sc[i] = __builtin_amdgcn_mfma_f32_16x16x32_bf16(qf[ks], kf, sc[i], 0, 0, 0);
;             }
; #pragma unroll
;         for (int i = 0; i < 8; ++i)
; #pragma unroll
.LBB0_104:
	s_andn2_b64 vcc, exec, s[0:1]
	s_cbranch_vccnz .LBB0_109
	v_readlane_b32 s0, v253, 4
	v_readlane_b32 s1, v253, 5
	s_waitcnt vmcnt(0)
	v_mov_b32_e32 v9, v221
	s_andn2_b64 vcc, exec, s[0:1]
	s_cbranch_vccnz .LBB0_109
	v_and_b32_e32 v14, 64, v220
	v_xor_b32_e32 v13, 1, v220
	v_add_u32_e32 v14, 64, v14
	v_cmp_lt_i32_e32 vcc, v13, v14
	v_ashrrev_i32_e32 v4, 6, v9
	s_movk_i32 s0, 0x1100
	v_cndmask_b32_e32 v13, v220, v13, vcc
	v_lshlrev_b32_e32 v98, 2, v13
	v_xor_b32_e32 v13, 2, v220
	v_cmp_lt_i32_e32 vcc, v13, v14
	v_mul_lo_u32 v0, v4, s0
	v_readlane_b32 s0, v253, 34
	v_cndmask_b32_e32 v13, v220, v13, vcc
	v_lshlrev_b32_e32 v99, 2, v13
	v_xor_b32_e32 v13, 4, v220
	v_cmp_lt_i32_e32 vcc, v13, v14
	v_add_u32_e32 v10, s0, v0
	v_lshlrev_b32_e32 v0, 4, v9
	v_cndmask_b32_e32 v13, v220, v13, vcc
	v_lshlrev_b32_e32 v100, 2, v13
	v_xor_b32_e32 v13, 8, v220
	v_and_b32_e32 v0, 0xf0, v0
	v_cmp_lt_i32_e32 vcc, v13, v14
	v_bfe_u32 v12, v9, 4, 2
	v_lshl_add_u64 v[2:3], s[80:81], 0, v[0:1]
	s_mov_b64 s[0:1], 0x20eb4000
	v_cndmask_b32_e32 v13, v220, v13, vcc
	v_lshl_add_u64 v[64:65], v[2:3], 0, s[0:1]
	v_writelane_b32 v254, s10, 37
	v_add_u32_e32 v5, 0, v0
	v_lshlrev_b32_e32 v2, 2, v12
	v_lshl_add_u64 v[68:69], s[10:11], 0, v[0:1]
	v_lshlrev_b32_e32 v0, 4, v4
	v_lshlrev_b32_e32 v101, 2, v13
	v_add_u32_e32 v13, 0x200, v9
	v_and_b32_e32 v11, 15, v9
	v_writelane_b32 v254, s11, 38
	v_or_b32_e32 v56, v2, v0
	s_movk_i32 s0, 0x110
	v_ashrrev_i32_e32 v62, 4, v9
	v_ashrrev_i32_e32 v66, 4, v13
	v_add_u32_e32 v13, 0x400, v9
	v_add_u32_e32 v9, 0x600, v9
	v_ashrrev_i32_e32 v55, 31, v0
	v_or_b32_e32 v54, v0, v11
	v_mul_u32_u24_e32 v8, 0x110, v11
	v_mad_u32_u24 v6, v11, s0, v10
	v_lshlrev_b32_e32 v2, 7, v11
	v_lshlrev_b32_e32 v0, 1, v11
	v_writelane_b32 v254, s26, 35
	v_ashrrev_i32_e32 v70, 4, v13
	v_ashrrev_i32_e32 v74, 4, v9
	v_or_b32_e32 v14, 16, v11
	v_or_b32_e32 v16, 32, v11
	v_or_b32_e32 v18, 48, v11
	v_or_b32_e32 v19, 64, v11
	v_or_b32_e32 v20, 0x50, v11
	v_or_b32_e32 v21, 0x60, v11
	v_or_b32_e32 v22, 0x70, v11
	v_sub_u32_e32 v11, v56, v11
	v_writelane_b32 v254, s27, 36
	v_readlane_b32 s4, v253, 63
	v_mul_lo_u32 v9, v62, s0
	v_mul_lo_u32 v13, v66, s0
	v_mul_lo_u32 v15, v70, s0
	v_mul_lo_u32 v17, v74, s0
	v_cmp_lt_i32_e64 s[0:1], -1, v11
	v_readlane_b32 s5, v254, 0
	v_lshl_add_u64 v[72:73], s[26:27], 0, v[0:1]
	v_writelane_b32 v254, s0, 19
	v_lshl_add_u64 v[76:77], s[4:5], 0, v[0:1]
	v_add_u32_e32 v23, v10, v0
	v_writelane_b32 v254, s1, 20
	v_cmp_gt_i32_e64 s[0:1], 1, v11
	v_sub_u32_e32 v0, 0, v11
	v_cvt_f32_u32_e32 v219, v0
	v_writelane_b32 v254, s0, 17
	v_add_u32_e32 v0, 1, v11
	v_cvt_f32_u32_e32 v215, v0
	v_writelane_b32 v254, s1, 18
	v_cmp_lt_i32_e64 s[0:1], -2, v11
	v_not_b32_e32 v0, v11
	v_cvt_f32_u32_e32 v218, v0
	v_writelane_b32 v254, s0, 15
	v_add_u32_e32 v0, 2, v11
	v_cvt_f32_u32_e32 v106, v0
	v_writelane_b32 v254, s1, 16
	v_cmp_gt_i32_e64 s[0:1], 0, v11
	v_sub_u32_e32 v0, -2, v11
	v_cvt_f32_u32_e32 v107, v0
	v_writelane_b32 v254, s0, 13
	v_add_u32_e32 v0, 3, v11
	v_cvt_f32_u32_e32 v108, v0
	v_writelane_b32 v254, s1, 14
	v_cmp_lt_i32_e64 s[0:1], -3, v11
	v_sub_u32_e32 v0, -3, v11
	v_cvt_f32_u32_e32 v109, v0
	v_writelane_b32 v254, s0, 11
	v_sub_u32_e32 v0, v56, v14
	v_lshlrev_b32_e32 v4, 3, v12
	v_writelane_b32 v254, s1, 12
	v_cmp_gt_i32_e64 s[0:1], -1, v11
	v_lshlrev_b32_e32 v3, 4, v12
	v_mul_u32_u24_e32 v24, 0x440, v12
	v_writelane_b32 v254, s0, 9
	v_sub_u32_e32 v12, 0, v0
	v_cvt_f32_u32_e32 v111, v12
	v_writelane_b32 v254, s1, 10
	v_cmp_lt_i32_e64 s[0:1], -4, v11
	v_add_u32_e32 v12, 1, v0
	v_cvt_f32_u32_e32 v112, v12
	v_writelane_b32 v254, s0, 7
	v_not_b32_e32 v12, v0
	v_cvt_f32_u32_e32 v113, v12
	v_writelane_b32 v254, s1, 8
	v_cmp_gt_i32_e64 s[0:1], -2, v11
	v_add_u32_e32 v12, 2, v0
	v_cvt_f32_u32_e32 v114, v12
	v_writelane_b32 v254, s0, 5
	v_sub_u32_e32 v12, -2, v0
	v_cvt_f32_u32_e32 v110, v0
	v_writelane_b32 v254, s1, 6
	v_cmp_lt_i32_e64 s[0:1], -1, v0
	v_cvt_f32_u32_e32 v115, v12
	v_add_u32_e32 v12, 3, v0
	v_writelane_b32 v254, s0, 3
	v_cvt_f32_u32_e32 v116, v12
	v_cvt_f32_u32_e32 v252, v11
	v_writelane_b32 v254, s1, 4
	v_cmp_gt_i32_e64 s[0:1], 1, v0
	v_lshl_add_u32 v11, v14, 1, v10
	v_lshl_add_u32 v25, v16, 1, v10
	v_writelane_b32 v254, s0, 1
	v_lshl_add_u32 v26, v18, 1, v10
	v_lshl_add_u32 v27, v20, 1, v10
	v_writelane_b32 v254, s1, 2
	v_cmp_lt_i32_e64 s[0:1], -2, v0
	v_lshl_add_u32 v28, v22, 1, v10
	s_add_u32 s2, s80, 0x1feb4000
	v_writelane_b32 v254, s0, 21
	v_add_u32_e32 v7, 0, v3
	v_or_b32_e32 v14, 0x1800, v2
	v_writelane_b32 v254, s1, 22
	v_cmp_gt_i32_e64 s[0:1], 0, v0
	s_addc_u32 s3, s81, 0
	v_mov_b32_e32 v57, v55
	v_writelane_b32 v254, s0, 25
	v_ashrrev_i32_e32 v63, 31, v62
	v_ashrrev_i32_e32 v67, 31, v66
	v_writelane_b32 v254, s1, 26
	v_cmp_lt_i32_e64 s[0:1], -3, v0
	v_ashrrev_i32_e32 v71, 31, v70
	v_ashrrev_i32_e32 v75, 31, v74
	v_writelane_b32 v254, s0, 31
	s_mov_b32 s15, 0x3f2aaaab
	v_add_u32_e32 v193, v5, v9
	v_writelane_b32 v254, s1, 32
	v_cmp_gt_i32_e64 s[0:1], -1, v0
	v_add_u32_e32 v194, v5, v13
	v_add_u32_e32 v195, v5, v15
	v_writelane_b32 v254, s0, 29
	v_add_u32_e32 v196, v5, v17
	v_add_u32_e32 v197, v7, v8
	v_writelane_b32 v254, s1, 30
	v_cmp_lt_i32_e64 s[0:1], -4, v0
	v_add_u32_e32 v198, v23, v24
	v_add_u32_e32 v199, v11, v24
	v_writelane_b32 v254, s0, 27
	v_add_u32_e32 v200, v25, v24
	v_add_u32_e32 v201, v26, v24
	v_writelane_b32 v254, s1, 28
	v_cmp_gt_i32_e64 s[0:1], -2, v0
	v_sub_u32_e32 v0, -3, v0
	v_cvt_f32_u32_e32 v117, v0
	v_writelane_b32 v254, s0, 33
	v_sub_u32_e32 v0, v56, v16
	v_sub_u32_e32 v12, 0, v0
	v_writelane_b32 v254, s1, 34
	v_cmp_lt_i32_e64 s[0:1], -1, v0
	v_cvt_f32_u32_e32 v119, v12
	v_add_u32_e32 v12, 1, v0
; #define LAS __attribute__((address_space(3)))
; __device__ __forceinline__ bf16_t f2bf(float x) { return (bf16_t)(cvt_pk_bf16(x, 0.f) & 0xffffu); }
; __device__ __forceinline__ void r2_phase(KP p, LAS unsigned char* lds, int G, int bid, int wv) {
;     ...
;         for (int i = 0; i < 8; ++i)
; #pragma unroll
;             for (int j = 0; j < 4; ++j) {
;                 const int diff = (16 * wid + 4 * fq + j) - (16 * i + fr);
;                 const float df = diff >= 0 ? __builtin_amdgcn_exp2f(lf * (float)diff) : 0.f;
;                 const float db = diff <= 0 ? __builtin_amdgcn_exp2f(lb * (float)(-diff)) : 0.f;
;                 *(LAS bf16_t*)(Pw + (4 * fq + j) * 272 + (16 * i + fr) * 2) = f2bf(sc[i][j] * (df + db));
	v_writelane_b32 v254, s0, 23
	v_cvt_f32_u32_e32 v120, v12
	v_not_b32_e32 v12, v0
	v_writelane_b32 v254, s1, 24
	v_cmp_gt_i32_e64 s[0:1], 1, v0
	v_cvt_f32_u32_e32 v121, v12
	v_add_u32_e32 v12, 2, v0
	v_writelane_b32 v254, s0, 39
	v_cvt_f32_u32_e32 v122, v12
	v_sub_u32_e32 v12, -2, v0
	v_writelane_b32 v254, s1, 40
	v_cmp_lt_i32_e64 s[0:1], -2, v0
	v_cvt_f32_u32_e32 v118, v0
	v_cvt_f32_u32_e32 v123, v12
	v_writelane_b32 v254, s0, 41
	v_add_u32_e32 v12, 3, v0
	v_cvt_f32_u32_e32 v124, v12
	v_writelane_b32 v254, s1, 42
	v_cmp_gt_i32_e64 s[0:1], 0, v0
	v_or_b32_e32 v16, 0x2000, v2
	v_add_u32_e32 v203, v27, v24
	v_writelane_b32 v254, s0, 43
	v_add_u32_e32 v205, v28, v24
	v_add_u32_e32 v206, v6, v3
	v_writelane_b32 v254, s1, 44
	v_cmp_lt_i32_e64 s[0:1], -3, v0
	v_lshlrev_b32_e32 v78, 1, v2
	v_lshlrev_b32_e32 v84, 1, v14
	v_writelane_b32 v254, s0, 45
	v_lshlrev_b32_e32 v86, 1, v16
	s_mov_b32 s12, 0xbfb8aa3b
	v_writelane_b32 v254, s1, 46
	v_cmp_gt_i32_e64 s[0:1], -1, v0
	s_mov_b32 s13, 0xc2b17218
	s_mov_b32 s14, 0x7f800000
	v_writelane_b32 v254, s0, 47
	s_mov_b32 s51, 0x3f317218
	s_mov_b32 s86, 0x33800000
	v_writelane_b32 v254, s1, 48
	v_cmp_lt_i32_e64 s[0:1], -4, v0
	s_mov_b32 s77, 0xf800000
	s_nop 0
	v_writelane_b32 v254, s0, 49
	s_nop 1
	v_writelane_b32 v254, s1, 50
	v_cmp_gt_i32_e64 s[0:1], -2, v0
	v_sub_u32_e32 v0, -3, v0
	v_cvt_f32_u32_e32 v125, v0
	v_writelane_b32 v254, s0, 51
	v_sub_u32_e32 v0, v56, v18
	v_sub_u32_e32 v12, 0, v0
	v_writelane_b32 v254, s1, 52
	v_cmp_lt_i32_e64 s[0:1], -1, v0
	v_cvt_f32_u32_e32 v127, v12
	v_add_u32_e32 v12, 1, v0
	v_writelane_b32 v254, s0, 53
	v_cvt_f32_u32_e32 v128, v12
	v_not_b32_e32 v12, v0
	v_writelane_b32 v254, s1, 54
	v_cmp_gt_i32_e64 s[0:1], 1, v0
	v_cvt_f32_u32_e32 v129, v12
	v_add_u32_e32 v12, 2, v0
	v_writelane_b32 v254, s0, 55
	v_cvt_f32_u32_e32 v130, v12
	v_sub_u32_e32 v12, -2, v0
	v_writelane_b32 v254, s1, 56
	v_cmp_lt_i32_e64 s[0:1], -2, v0
	v_cvt_f32_u32_e32 v126, v0
	v_cvt_f32_u32_e32 v131, v12
	v_writelane_b32 v254, s0, 57
	v_add_u32_e32 v12, 3, v0
	v_cvt_f32_u32_e32 v132, v12
	v_writelane_b32 v254, s1, 58
	v_cmp_gt_i32_e64 s[0:1], 0, v0
	v_or_b32_e32 v18, 0x2800, v2
	v_lshlrev_b32_e32 v88, 1, v18
	v_writelane_b32 v254, s0, 59
	s_nop 1
	v_writelane_b32 v254, s1, 60
	v_cmp_lt_i32_e64 s[0:1], -3, v0
	s_nop 1
	v_writelane_b32 v254, s0, 61
	s_nop 1
	v_writelane_b32 v254, s1, 62
	v_cmp_gt_i32_e64 s[0:1], -1, v0
	s_nop 1
	v_writelane_b32 v254, s0, 63
	s_nop 1
	v_writelane_b32 v255, s1, 0
	v_cmp_lt_i32_e64 s[0:1], -4, v0
	s_nop 1
	v_writelane_b32 v255, s0, 1
	s_nop 1
	v_writelane_b32 v255, s1, 2
	v_cmp_gt_i32_e64 s[0:1], -2, v0
	v_sub_u32_e32 v0, -3, v0
	v_cvt_f32_u32_e32 v133, v0
	v_writelane_b32 v255, s0, 3
	v_sub_u32_e32 v0, v56, v19
	v_sub_u32_e32 v12, 0, v0
	v_writelane_b32 v255, s1, 4
	v_cmp_lt_i32_e64 s[0:1], -1, v0
	v_cvt_f32_u32_e32 v135, v12
	v_add_u32_e32 v12, 1, v0
	v_writelane_b32 v255, s0, 5
	v_cvt_f32_u32_e32 v136, v12
	v_not_b32_e32 v12, v0
	v_writelane_b32 v255, s1, 6
	v_cmp_gt_i32_e64 s[0:1], 1, v0
	v_cvt_f32_u32_e32 v137, v12
	v_add_u32_e32 v12, 2, v0
	v_writelane_b32 v255, s0, 7
	v_cvt_f32_u32_e32 v138, v12
	v_sub_u32_e32 v12, -2, v0
	v_writelane_b32 v255, s1, 8
	v_cmp_lt_i32_e64 s[0:1], -2, v0
	v_cvt_f32_u32_e32 v134, v0
	v_cvt_f32_u32_e32 v139, v12
	v_writelane_b32 v255, s0, 9
	v_add_u32_e32 v12, 3, v0
	v_cvt_f32_u32_e32 v140, v12
	v_writelane_b32 v255, s1, 10
	v_cmp_gt_i32_e64 s[0:1], 0, v0
	v_lshl_add_u32 v19, v19, 1, v10
	v_add_u32_e32 v202, v19, v24
	v_writelane_b32 v255, s0, 11
	s_nop 1
	v_writelane_b32 v255, s1, 12
	v_cmp_lt_i32_e64 s[0:1], -3, v0
	s_nop 1
	v_writelane_b32 v255, s0, 13
	s_nop 1
	v_writelane_b32 v255, s1, 14
	v_cmp_gt_i32_e64 s[0:1], -1, v0
	s_nop 1
	v_writelane_b32 v255, s0, 15
	s_nop 1
	v_writelane_b32 v255, s1, 16
	v_cmp_lt_i32_e64 s[0:1], -4, v0
	s_nop 1
	v_writelane_b32 v255, s0, 17
	s_nop 1
	v_writelane_b32 v255, s1, 18
	v_cmp_gt_i32_e64 s[0:1], -2, v0
	v_sub_u32_e32 v0, -3, v0
	v_cvt_f32_u32_e32 v141, v0
	v_writelane_b32 v255, s0, 19
	v_sub_u32_e32 v0, v56, v20
	v_sub_u32_e32 v12, 0, v0
; __device__ __forceinline__ void r2_phase(KP p, LAS unsigned char* lds, int G, int bid, int wv) {
;     ...
;     for (int u = bid; u < 512; u += G) {
;         const int bh = u >> 4, n = u & 15, b = bh >> 3, h = bh & 7;
;     ...
;         for (int j = 0; j < 4; ++j) { const int c = 16 * wid + 4 * fq + j; sfac[j] = __builtin_amdgcn_exp2f(lf * (float)(c + 1)); sbac[j] = __builtin_amdgcn_exp2f(lb * (float)(128 - c)); }
	v_writelane_b32 v255, s1, 20
	v_cmp_lt_i32_e64 s[0:1], -1, v0
	v_cvt_f32_u32_e32 v143, v12
	v_add_u32_e32 v12, 1, v0
	v_writelane_b32 v255, s0, 21
	v_cvt_f32_u32_e32 v144, v12
	v_not_b32_e32 v12, v0
	v_writelane_b32 v255, s1, 22
	v_cmp_gt_i32_e64 s[0:1], 1, v0
	v_cvt_f32_u32_e32 v145, v12
	v_add_u32_e32 v12, 2, v0
	v_writelane_b32 v255, s0, 23
	v_cvt_f32_u32_e32 v146, v12
	v_sub_u32_e32 v12, -2, v0
	v_writelane_b32 v255, s1, 24
	v_cmp_lt_i32_e64 s[0:1], -2, v0
	v_cvt_f32_u32_e32 v142, v0
	v_cvt_f32_u32_e32 v147, v12
	v_writelane_b32 v255, s0, 25
	v_add_u32_e32 v12, 3, v0
	v_cvt_f32_u32_e32 v148, v12
	v_writelane_b32 v255, s1, 26
	v_cmp_gt_i32_e64 s[0:1], 0, v0
	v_or_b32_e32 v20, 0x3000, v2
	v_lshlrev_b32_e32 v90, 1, v20
	v_writelane_b32 v255, s0, 27
	s_nop 1
	v_writelane_b32 v255, s1, 28
	v_cmp_lt_i32_e64 s[0:1], -3, v0
	s_nop 1
	v_writelane_b32 v255, s0, 29
	s_nop 1
	v_writelane_b32 v255, s1, 30
	v_cmp_gt_i32_e64 s[0:1], -1, v0
	s_nop 1
	v_writelane_b32 v255, s0, 31
	s_nop 1
	v_writelane_b32 v255, s1, 32
	v_cmp_lt_i32_e64 s[0:1], -4, v0
	s_nop 1
	v_writelane_b32 v255, s0, 33
	s_nop 1
	v_writelane_b32 v255, s1, 34
	v_cmp_gt_i32_e64 s[0:1], -2, v0
	v_sub_u32_e32 v0, -3, v0
	v_cvt_f32_u32_e32 v149, v0
	v_writelane_b32 v255, s0, 35
	v_sub_u32_e32 v0, v56, v21
	v_sub_u32_e32 v12, 0, v0
	v_writelane_b32 v255, s1, 36
	v_cmp_lt_i32_e64 s[0:1], -1, v0
	v_cvt_f32_u32_e32 v151, v12
	v_add_u32_e32 v12, 1, v0
	v_writelane_b32 v255, s0, 37
	v_cvt_f32_u32_e32 v152, v12
	v_not_b32_e32 v12, v0
	v_writelane_b32 v255, s1, 38
	v_cmp_gt_i32_e64 s[0:1], 1, v0
	v_cvt_f32_u32_e32 v153, v12
	v_add_u32_e32 v12, 2, v0
	v_writelane_b32 v255, s0, 39
	v_cvt_f32_u32_e32 v154, v12
	v_sub_u32_e32 v12, -2, v0
	v_writelane_b32 v255, s1, 40
	v_cmp_lt_i32_e64 s[0:1], -2, v0
	v_cvt_f32_u32_e32 v150, v0
	v_cmp_lt_i32_e64 s[6:7], -3, v0
	v_writelane_b32 v255, s0, 41
	v_cmp_gt_i32_e64 s[54:55], -1, v0
	v_cvt_f32_u32_e32 v155, v12
	v_writelane_b32 v255, s1, 42
	v_cmp_gt_i32_e64 s[0:1], 0, v0
	v_add_u32_e32 v12, 3, v0
	v_cmp_lt_i32_e64 s[64:65], -4, v0
	v_cmp_gt_i32_e64 s[20:21], -2, v0
	v_sub_u32_e32 v0, -3, v0
	v_cvt_f32_u32_e32 v157, v0
	v_sub_u32_e32 v0, v56, v22
	v_lshl_add_u32 v21, v21, 1, v10
	v_sub_u32_e32 v10, 0, v0
	v_cvt_f32_u32_e32 v159, v10
	v_add_u32_e32 v10, 1, v0
	v_cvt_f32_u32_e32 v160, v10
	v_not_b32_e32 v10, v0
	v_cvt_f32_u32_e32 v161, v10
	v_add_u32_e32 v10, 2, v0
	v_cvt_f32_u32_e32 v163, v10
	v_sub_u32_e32 v10, -2, v0
	v_cmp_lt_i32_e64 s[22:23], -1, v0
	v_cvt_f32_u32_e32 v158, v0
	v_cmp_gt_i32_e64 s[24:25], 1, v0
	v_cmp_lt_i32_e64 s[26:27], -2, v0
	v_cmp_gt_i32_e64 s[28:29], 0, v0
	v_cmp_lt_i32_e64 s[30:31], -3, v0
	v_cmp_gt_i32_e64 s[34:35], -1, v0
	v_cvt_f32_u32_e32 v178, v10
	v_add_u32_e32 v10, 3, v0
	v_cmp_lt_i32_e64 s[36:37], -4, v0
	v_cmp_gt_i32_e64 s[38:39], -2, v0
	v_sub_u32_e32 v0, -3, v0
	v_cvt_f32_u32_e32 v182, v10
	v_cvt_f32_u32_e32 v184, v0
	v_or_b32_e32 v0, 1, v56
	v_sub_u32_e32 v10, 0x80, v56
	v_cvt_f32_i32_e32 v185, v0
	v_cvt_f32_i32_e32 v186, v10
	v_or_b32_e32 v10, 2, v56
	v_sub_u32_e32 v0, 0x80, v0
	v_cvt_f32_i32_e32 v187, v10
	v_cvt_f32_i32_e32 v188, v0
	v_or_b32_e32 v0, 3, v56
	v_sub_u32_e32 v10, 0x80, v10
	v_cvt_f32_i32_e32 v189, v0
	v_cvt_f32_i32_e32 v190, v10
	v_add_u32_e32 v10, 4, v56
	v_sub_u32_e32 v0, 0x80, v0
	v_cvt_f32_u32_e32 v156, v12
	v_cvt_f32_i32_e32 v191, v10
	v_cvt_f32_i32_e32 v192, v0
	v_writelane_b32 v255, s0, 43
	v_or_b32_e32 v10, 0x800, v2
	v_or_b32_e32 v12, 0x1000, v2
	v_or_b32_e32 v22, 0x3800, v2
	v_writelane_b32 v255, s1, 44
	v_lshlrev_b32_e32 v0, 1, v4
	v_add_u32_e32 v204, v21, v24
	v_lshlrev_b32_e32 v80, 1, v10
	v_lshlrev_b32_e32 v82, 1, v12
	v_lshlrev_b32_e32 v92, 1, v22
	s_bfe_u32 s0, s33, 0x20001
	s_lshl_b32 s0, s0, 3
	s_and_b32 s1, s33, 1
	s_lshl_b32 s1, s1, 1
	s_or_b32 s0, s0, s1
	s_lshr_b32 s1, s33, 6
	s_and_b32 s4, s1, 1
	s_or_b32 s0, s0, s4
	s_lshr_b32 s1, s1, 1
	s_lshl_b32 s1, s1, 2
	s_or_b32 s0, s0, s1
	s_bfe_u32 s1, s33, 0x30003
	s_lshl_b32 s0, s0, 4
	s_add_i32 s0, s0, s1
	s_cmp_eq_u32 s42, 0x100
	s_cselect_b32 s0, s0, s33

; __device__ __forceinline__ void r1s_sweep(const bf16_t* __restrict__ kT, const bf16_t* __restrict__ vT, bf16_t* __restrict__ STd, int bh, int s, int wid, int fr, int fq, float lg, float gC, bool fwd) {
;     float w[4][8];
; #pragma unroll
;     for (int ks = 0; ks < 4; ++ks)
; #pragma unroll
;         for (int e = 0; e < 8; ++e) { const int t = 32 * ks + 8 * fq + e; w[ks][e] = __builtin_amdgcn_exp2f(lg * (float)(fwd ? 127 - t : t)); }
;     f32x4 S = {0.f, 0.f, 0.f, 0.f};
;     const size_t koff = (size_t)(16 * s + fr) * 128 + 8 * fq, voff = (size_t)(16 * wid + fr) * 128 + 8 * fq;
; __device__ __forceinline__ void r1s_phase(KP p, int G, int bid, int wv) {
;     ...
;     for (int u = bid; u < 256; u += G) {
;         const int bh = u >> 3, s = u & 7, h = bh & 7;
.LBB0_110:
	s_andn2_b64 vcc, exec, s[0:1]
	s_cbranch_vccnz .LBB0_122
	v_writelane_b32 v254, s26, 35
	v_mov_b32_e32 v252, 0x3727c5ac
	v_mov_b32_e32 v93, v221
	v_writelane_b32 v254, s27, 36
	s_andn2_b64 vcc, exec, s[58:59]
	s_mov_b32 s12, 0xbfb8aa3b
	s_mov_b32 s13, 0xc2b17218
	s_mov_b32 s14, 0x7f800000
	s_mov_b32 s15, 0x3f317218
	s_mov_b32 s22, 0x33800000
	s_mov_b32 s23, 0x8000
	s_mov_b32 s24, 0x18000
	s_mov_b32 s25, 0x28000
	s_mov_b32 s26, 0x30000
	s_mov_b32 s27, 0x38000
	s_mov_b32 s29, 0x40000
	s_mov_b32 s30, 0x48000
	s_mov_b32 s31, 0x50000
	s_mov_b32 s34, 0x58000
	s_mov_b32 s36, 0x60000
	s_mov_b32 s37, 0x68000
	s_mov_b32 s38, 0x70000
	s_mov_b32 s39, 0x78000
	s_cbranch_vccnz .LBB0_114
	v_bfe_u32 v0, v93, 4, 2
	v_lshlrev_b32_e32 v126, 3, v0
	s_waitcnt vmcnt(0)
	v_xor_b32_e32 v2, 0x7f, v126
	v_cvt_f32_ubyte0_e32 v127, v2
	v_xor_b32_e32 v2, 0x7e, v126
	v_cvt_f32_ubyte0_e32 v128, v2
	v_xor_b32_e32 v2, 0x7d, v126
	v_cvt_f32_ubyte0_e32 v129, v2
	v_xor_b32_e32 v2, 0x7c, v126
	v_cvt_f32_ubyte0_e32 v130, v2
	v_xor_b32_e32 v2, 0x7b, v126
	v_cvt_f32_ubyte0_e32 v131, v2
	v_xor_b32_e32 v2, 0x7a, v126
	v_cvt_f32_ubyte0_e32 v132, v2
	v_xor_b32_e32 v2, 0x79, v126
	v_cvt_f32_ubyte0_e32 v133, v2
	v_xor_b32_e32 v2, 0x78, v126
	v_cvt_f32_ubyte0_e32 v134, v2
	v_xor_b32_e32 v2, 0x5f, v126
	v_cvt_f32_ubyte0_e32 v135, v2
	v_xor_b32_e32 v2, 0x5e, v126
	v_cvt_f32_ubyte0_e32 v136, v2
	v_xor_b32_e32 v2, 0x5d, v126
	v_cvt_f32_ubyte0_e32 v137, v2
	v_xor_b32_e32 v2, 0x5c, v126
	v_cvt_f32_ubyte0_e32 v138, v2
	v_xor_b32_e32 v2, 0x5b, v126
	v_cvt_f32_ubyte0_e32 v139, v2
	v_xor_b32_e32 v2, 0x5a, v126
	v_cvt_f32_ubyte0_e32 v140, v2
	v_xor_b32_e32 v2, 0x59, v126
	v_cvt_f32_ubyte0_e32 v141, v2
	v_xor_b32_e32 v2, 0x58, v126
	v_cvt_f32_ubyte0_e32 v142, v2
	v_xor_b32_e32 v2, 63, v126
	v_cvt_f32_ubyte0_e32 v143, v2
	v_xor_b32_e32 v2, 62, v126
	v_cvt_f32_ubyte0_e32 v144, v2
	v_xor_b32_e32 v2, 61, v126
	v_cvt_f32_ubyte0_e32 v145, v2
	v_xor_b32_e32 v2, 60, v126
	v_cvt_f32_ubyte0_e32 v146, v2
	v_xor_b32_e32 v2, 59, v126
	v_cvt_f32_ubyte0_e32 v147, v2
	v_xor_b32_e32 v2, 58, v126
	v_cvt_f32_ubyte0_e32 v148, v2
	v_xor_b32_e32 v2, 57, v126
	v_cvt_f32_ubyte0_e32 v149, v2
	v_xor_b32_e32 v2, 56, v126
	v_cvt_f32_ubyte0_e32 v150, v2
	v_xor_b32_e32 v2, 31, v126
	v_cvt_f32_ubyte0_e32 v151, v2
	v_xor_b32_e32 v2, 30, v126
	v_cvt_f32_ubyte0_e32 v152, v2
	v_xor_b32_e32 v2, 29, v126
	v_cvt_f32_ubyte0_e32 v153, v2
	v_xor_b32_e32 v2, 28, v126
	v_cvt_f32_ubyte0_e32 v154, v2
	v_xor_b32_e32 v2, 27, v126
	v_cvt_f32_ubyte0_e32 v155, v2
	v_xor_b32_e32 v2, 26, v126
	v_cvt_f32_ubyte0_e32 v156, v2
	v_xor_b32_e32 v2, 25, v126
	v_cvt_f32_ubyte0_e32 v157, v2
	v_xor_b32_e32 v2, 24, v126
	v_cvt_f32_ubyte0_e32 v158, v2
	v_ashrrev_i32_e32 v2, 2, v93
	v_bfi_b32 v2, -16, v2, v93
	v_ashrrev_i32_e32 v3, 31, v2
	v_lshlrev_b32_e32 v4, 7, v2
	v_ashrrev_i32_e32 v5, 31, v4
	v_lshlrev_b64 v[2:3], 8, v[2:3]
	v_lshl_add_u64 v[50:51], v[4:5], 1, s[8:9]
	v_lshlrev_b32_e32 v4, 2, v0
	v_lshl_add_u64 v[2:3], s[10:11], 0, v[2:3]
	v_lshlrev_b32_e32 v0, 4, v0
	v_lshl_add_u64 v[52:53], v[2:3], 0, v[0:1]
	v_or_b32_e32 v0, 1, v126
	v_cvt_f32_ubyte0_e32 v159, v0
	v_or_b32_e32 v0, 2, v126
	v_cvt_f32_ubyte0_e32 v160, v0
	v_or_b32_e32 v0, 3, v126
	v_cvt_f32_ubyte0_e32 v161, v0
	v_or_b32_e32 v0, 4, v126
	v_cvt_f32_ubyte0_e32 v178, v0
	v_or_b32_e32 v0, 5, v126
	v_cvt_f32_ubyte0_e32 v182, v0
	v_or_b32_e32 v0, 6, v126
	v_cvt_f32_ubyte0_e32 v184, v0
	v_or_b32_e32 v0, 7, v126
	v_cvt_f32_ubyte0_e32 v185, v0
	v_or_b32_e32 v0, 32, v126
	v_cvt_f32_ubyte0_e32 v186, v0
	v_or_b32_e32 v0, 33, v126
	v_cvt_f32_ubyte0_e32 v187, v0
	v_or_b32_e32 v0, 34, v126
	v_cvt_f32_ubyte0_e32 v188, v0
	v_or_b32_e32 v0, 35, v126
	v_cvt_f32_ubyte0_e32 v189, v0
	v_or_b32_e32 v0, 36, v126
	v_cvt_f32_ubyte0_e32 v190, v0
	v_or_b32_e32 v0, 37, v126
	v_cvt_f32_ubyte0_e32 v191, v0
	v_or_b32_e32 v0, 38, v126
	v_cvt_f32_ubyte0_e32 v192, v0
	v_or_b32_e32 v0, 39, v126
	v_cvt_f32_ubyte0_e32 v193, v0
	v_or_b32_e32 v0, 64, v126
	v_cvt_f32_ubyte0_e32 v194, v0
	v_or_b32_e32 v0, 0x41, v126
	v_cvt_f32_ubyte0_e32 v195, v0
	v_or_b32_e32 v0, 0x42, v126
	v_cvt_f32_ubyte0_e32 v196, v0
	v_or_b32_e32 v0, 0x43, v126
	v_cvt_f32_ubyte0_e32 v197, v0
	v_or_b32_e32 v0, 0x44, v126
	v_cvt_f32_ubyte0_e32 v198, v0
	v_or_b32_e32 v0, 0x45, v126
	v_cvt_f32_ubyte0_e32 v199, v0
	v_or_b32_e32 v0, 0x46, v126
	v_cvt_f32_ubyte0_e32 v200, v0
	v_or_b32_e32 v0, 0x47, v126
	v_cvt_f32_ubyte0_e32 v201, v0
	v_or_b32_e32 v0, 0x60, v126
	v_cvt_f32_ubyte0_e32 v202, v0
	v_or_b32_e32 v0, 0x61, v126
	v_cvt_f32_ubyte0_e32 v203, v0
	v_or_b32_e32 v0, 0x62, v126
	v_cvt_f32_ubyte0_e32 v204, v0
	v_or_b32_e32 v0, 0x63, v126
	s_load_dwordx4 s[4:7], s[78:79], 0x90
	v_cvt_f32_ubyte0_e32 v205, v0
	v_or_b32_e32 v0, 0x64, v126
	v_cvt_f32_ubyte0_e32 v206, v0
	v_or_b32_e32 v0, 0x65, v126
	v_cvt_f32_ubyte0_e32 v207, v0
	v_or_b32_e32 v0, 0x66, v126
	s_add_u32 s2, s80, 0x21eb4000
	v_cvt_f32_ubyte0_e32 v208, v0
	v_or_b32_e32 v0, 0x67, v126
	s_addc_u32 s3, s81, 0
	v_cvt_f32_ubyte0_e32 v209, v0
	v_lshlrev_b32_e32 v0, 1, v4
	v_readlane_b32 s0, v253, 27
	s_bfe_u32 s8, s33, 0x20001
	s_lshl_b32 s8, s8, 3
	s_and_b32 s9, s33, 1
	s_lshl_b32 s9, s9, 1
	s_or_b32 s8, s8, s9
	s_lshr_b32 s9, s33, 6
	s_and_b32 s10, s9, 1
	s_or_b32 s8, s8, s10
	s_lshr_b32 s9, s9, 1
	s_lshl_b32 s9, s9, 2
	s_or_b32 s8, s8, s9
	s_bfe_u32 s10, s33, 0x30003
	s_lshl_b32 s8, s8, 3
	s_add_i32 s8, s8, s10
	s_cmp_eq_u32 s42, 0x100
	s_cselect_b32 s1, s8, s33
